# step8 + hoisted x loads in the P0 x-to-bf16/gate loop (16 loads per iteration up front, counted waits) + final LayerNorm loop with loop-invariant gamma/beta loads hoisted out and all row loads issued
# baseline (speedup 1.0000x reference)
.LBB0_240:
	v_lshl_add_u64 v[52:53], v[14:15], 0, s[8:9]
	global_load_dwordx4 v[60:63], v[52:53], off
	global_load_dwordx4 v[64:67], v[52:53], off offset:16
	global_load_dwordx4 v[68:71], v[52:53], off offset:128
	global_load_dwordx4 v[72:75], v[52:53], off offset:144
	global_load_dwordx4 v[76:79], v[52:53], off offset:256
	global_load_dwordx4 v[80:83], v[52:53], off offset:272
	global_load_dwordx4 v[84:87], v[52:53], off offset:384
	global_load_dwordx4 v[88:91], v[52:53], off offset:400
	global_load_dwordx4 v[92:95], v[52:53], off offset:512
	global_load_dwordx4 v[96:99], v[52:53], off offset:528
	global_load_dwordx4 v[100:103], v[52:53], off offset:640
	global_load_dwordx4 v[104:107], v[52:53], off offset:656
	global_load_dwordx4 v[108:111], v[52:53], off offset:768
	global_load_dwordx4 v[112:115], v[52:53], off offset:784
	global_load_dwordx4 v[116:119], v[52:53], off offset:896
	global_load_dwordx4 v[120:123], v[52:53], off offset:912
	s_nop 0
	s_nop 0
	s_add_u32 s8, s8, 0x400
	s_addc_u32 s9, s9, 0
	s_cmpk_eq_i32 s8, 0x800
	s_waitcnt vmcnt(15)
	v_cvt_pk_bf16_f32 v20, v60, v61
	v_cvt_pk_bf16_f32 v21, v62, v63
	s_waitcnt vmcnt(14)
	v_cvt_pk_bf16_f32 v22, v64, v65
	v_cvt_pk_bf16_f32 v23, v66, v67
	global_store_dwordx4 v[12:13], v[20:23], off offset:-256
	s_nop 0
	s_nop 0
	s_waitcnt vmcnt(14)
	v_cvt_pk_bf16_f32 v24, v68, v69
	v_cvt_pk_bf16_f32 v25, v70, v71
	s_waitcnt vmcnt(13)
	v_cvt_pk_bf16_f32 v26, v72, v73
	v_cvt_pk_bf16_f32 v27, v74, v75
	global_store_dwordx4 v[12:13], v[24:27], off offset:-192
	s_nop 0
	s_nop 0
	s_waitcnt vmcnt(13)
	v_cvt_pk_bf16_f32 v28, v76, v77
	v_cvt_pk_bf16_f32 v29, v78, v79
	s_waitcnt vmcnt(12)
	v_cvt_pk_bf16_f32 v30, v80, v81
	v_cvt_pk_bf16_f32 v31, v82, v83
	global_store_dwordx4 v[12:13], v[28:31], off offset:-128
	s_nop 0
	s_nop 0
	s_waitcnt vmcnt(12)
	v_cvt_pk_bf16_f32 v32, v84, v85
	v_cvt_pk_bf16_f32 v33, v86, v87
	s_waitcnt vmcnt(11)
	v_cvt_pk_bf16_f32 v34, v88, v89
	v_cvt_pk_bf16_f32 v35, v90, v91
	global_store_dwordx4 v[12:13], v[32:35], off offset:-64
	s_nop 0
	s_nop 0
	ds_read_b128 v[44:47], v19
	ds_read_b128 v[48:51], v19 offset:64
	s_waitcnt lgkmcnt(1)
	v_mfma_f32_16x16x32_bf16 v[0:3], v[20:23], v[44:47], v[0:3]
	s_waitcnt vmcnt(11)
	v_cvt_pk_bf16_f32 v20, v92, v93
	v_cvt_pk_bf16_f32 v21, v94, v95
	s_waitcnt vmcnt(10)
	v_cvt_pk_bf16_f32 v22, v96, v97
	v_cvt_pk_bf16_f32 v23, v98, v99
	global_store_dwordx4 v[12:13], v[20:23], off
	s_nop 0
	s_nop 0
	s_waitcnt lgkmcnt(0)
	v_mfma_f32_16x16x32_bf16 v[0:3], v[24:27], v[48:51], v[0:3]
	ds_read_b128 v[24:27], v19 offset:128
	ds_read_b128 v[44:47], v19 offset:192
	s_waitcnt lgkmcnt(1)
	v_mfma_f32_16x16x32_bf16 v[0:3], v[28:31], v[24:27], v[0:3]
	s_waitcnt vmcnt(10)
	v_cvt_pk_bf16_f32 v24, v100, v101
	v_cvt_pk_bf16_f32 v25, v102, v103
	s_waitcnt vmcnt(9)
	v_cvt_pk_bf16_f32 v26, v104, v105
	v_cvt_pk_bf16_f32 v27, v106, v107
	global_store_dwordx4 v[12:13], v[24:27], off offset:64
	s_nop 0
	s_nop 0
	s_waitcnt lgkmcnt(0)
	v_mfma_f32_16x16x32_bf16 v[0:3], v[32:35], v[44:47], v[0:3]
	ds_read_b128 v[32:35], v19 offset:256
	ds_read_b128 v[40:43], v19 offset:320
	s_waitcnt lgkmcnt(1)
	v_mfma_f32_16x16x32_bf16 v[0:3], v[20:23], v[32:35], v[0:3]
	s_waitcnt vmcnt(9)
	v_cvt_pk_bf16_f32 v20, v108, v109
	v_cvt_pk_bf16_f32 v21, v110, v111
	s_waitcnt vmcnt(8)
	v_cvt_pk_bf16_f32 v22, v112, v113
	v_cvt_pk_bf16_f32 v23, v114, v115
	global_store_dwordx4 v[12:13], v[20:23], off offset:128
	s_nop 0
	s_nop 0
	ds_read_b128 v[36:39], v19 offset:384
	ds_read_b128 v[44:47], v19 offset:448
	s_waitcnt lgkmcnt(2)
	v_mfma_f32_16x16x32_bf16 v[0:3], v[24:27], v[40:43], v[0:3]
	v_add_u32_e32 v19, 0x200, v19
	s_waitcnt vmcnt(8)
	v_cvt_pk_bf16_f32 v24, v116, v117
	v_cvt_pk_bf16_f32 v25, v118, v119
	s_waitcnt vmcnt(7)
	v_cvt_pk_bf16_f32 v26, v120, v121
	v_cvt_pk_bf16_f32 v27, v122, v123
	s_waitcnt lgkmcnt(1)
	v_mfma_f32_16x16x32_bf16 v[0:3], v[20:23], v[36:39], v[0:3]
	global_store_dwordx4 v[12:13], v[24:27], off offset:192
	v_lshl_add_u64 v[12:13], v[12:13], 0, s[6:7]
	s_waitcnt lgkmcnt(0)
	v_mfma_f32_16x16x32_bf16 v[0:3], v[24:27], v[44:47], v[0:3]
	s_cbranch_scc0 .LBB0_240
	v_lshlrev_b32_e32 v12, 2, v158
	v_and_b32_e32 v12, -16, v12
	v_ashrrev_i32_e32 v13, 31, v12
	v_lshl_add_u64 v[12:13], v[12:13], 0, v[4:5]
	v_add_u32_e32 v158, s46, v158
	v_lshlrev_b64 v[12:13], 6, v[12:13]
	v_cmp_lt_i32_e32 vcc, s11, v158
	v_lshl_add_u64 v[12:13], v[6:7], 0, v[12:13]
	s_or_b64 s[4:5], vcc, s[4:5]
	v_add_u32_e32 v18, s10, v18
	global_store_dword v[12:13], v0, off
	global_store_dword v[12:13], v1, off offset:64
	global_store_dword v[12:13], v2, off offset:128
	global_store_dword v[12:13], v3, off offset:192
	s_andn2_b64 exec, exec, s[4:5]
	s_cbranch_execnz .LBB0_239

.LBB0_1547:
	s_or_b64 exec, exec, s[0:1]
	s_waitcnt lgkmcnt(0)
	s_barrier
	v_readlane_b32 s0, v251, 9
	v_ashrrev_i32_e32 v0, 6, v220
	s_nop 0
	v_add_u32_e32 v0, s0, v0
	s_movk_i32 s0, 0x4000
	v_cmp_gt_i32_e32 vcc, s0, v0
	s_and_saveexec_b64 s[0:1], vcc
	s_cbranch_execz .LBB0_1550
	s_add_u32 s0, s70, 0x2000
	s_addc_u32 s1, s71, 0
	v_lshlrev_b32_e32 v1, 5, v220
	s_add_u32 s2, s68, 0x2000
	v_and_b32_e32 v16, 0x7e0, v1
	v_ashrrev_i32_e32 v1, 31, v0
	s_addc_u32 s3, s69, 0
	v_mov_b32_e32 v17, 0
	v_and_b32_e32 v24, 63, v220
	v_lshlrev_b64 v[22:23], 13, v[0:1]
	v_lshl_add_u64 v[2:3], s[2:3], 0, v[16:17]
	v_lshl_add_u64 v[4:5], s[0:1], 0, v[16:17]
	v_or_b32_e32 v8, 0x800, v16
	v_mov_b32_e32 v9, v17
	v_or_b32_e32 v12, 0x1000, v16
	v_mov_b32_e32 v13, v17
	v_or_b32_e32 v16, 0x1800, v16
	v_lshl_or_b32 v22, v24, 5, v22
	v_lshl_add_u64 v[6:7], s[2:3], 0, v[8:9]
	v_lshl_add_u64 v[8:9], s[0:1], 0, v[8:9]
	v_lshl_add_u64 v[10:11], s[2:3], 0, v[12:13]
	v_lshl_add_u64 v[12:13], s[0:1], 0, v[12:13]
	v_lshl_add_u64 v[14:15], s[2:3], 0, v[16:17]
	v_lshl_add_u64 v[16:17], s[0:1], 0, v[16:17]
	v_lshlrev_b64 v[18:19], 12, v[0:1]
	s_ashr_i32 s47, s46, 31
	v_mov_b64_e32 v[20:21], 0x1fba0000
	v_lshl_add_u64 v[22:23], s[72:73], 0, v[22:23]
	s_mov_b64 s[0:1], 0x1000
	v_lshl_or_b32 v18, v24, 4, v18
	s_lshl_b64 s[2:3], s[46:47], 12
	v_lshl_add_u64 v[20:21], v[0:1], 3, v[20:21]
	s_lshl_b64 s[4:5], s[46:47], 3
	v_lshl_add_u64 v[22:23], v[22:23], 0, s[0:1]
	s_lshl_b64 s[6:7], s[46:47], 13
	s_mov_b64 s[8:9], 0
	s_mov_b32 s10, 0x3a000000
	s_mov_b32 s11, 0xf800000
	v_mov_b32_e32 v1, 0x260
	s_mov_b32 s12, 0xbb00000
	s_movk_i32 s13, 0x3fff
	global_load_dwordx4 v[64:67], v[2:3], off offset:16
	global_load_dwordx4 v[68:71], v[2:3], off
	global_load_dwordx4 v[72:75], v[4:5], off offset:16
	global_load_dwordx4 v[76:79], v[4:5], off
	global_load_dwordx4 v[80:83], v[8:9], off
	global_load_dwordx4 v[84:87], v[6:7], off
	global_load_dwordx4 v[88:91], v[6:7], off offset:16
	global_load_dwordx4 v[92:95], v[8:9], off offset:16
	global_load_dwordx4 v[96:99], v[12:13], off
	global_load_dwordx4 v[100:103], v[10:11], off
	global_load_dwordx4 v[104:107], v[10:11], off offset:16
	global_load_dwordx4 v[108:111], v[12:13], off offset:16
	global_load_dwordx4 v[112:115], v[16:17], off
	global_load_dwordx4 v[116:119], v[14:15], off
	global_load_dwordx4 v[120:123], v[14:15], off offset:16
	global_load_dwordx4 v[124:127], v[16:17], off offset:16
	s_waitcnt vmcnt(0)
.LBB0_1549:
	v_lshl_add_u64 v[24:25], s[74:75], 0, v[20:21]
	v_lshl_add_u64 v[42:43], s[74:75], 0, v[18:19]
	s_nop 0
	s_nop 0
	s_nop 0
	s_nop 0
	global_load_dwordx2 v[46:47], v[24:25], off
	v_add_co_u32_e32 v48, vcc, s12, v42
	v_add_u32_e32 v0, s46, v0
	s_nop 0
	v_addc_co_u32_e32 v49, vcc, 0, v43, vcc
	global_load_dwordx4 v[42:45], v[48:49], off
	global_load_dwordx4 v[128:131], v[48:49], off offset:1024
	global_load_dwordx4 v[132:135], v[48:49], off offset:2048
	global_load_dwordx4 v[136:139], v[48:49], off offset:3072
	v_lshl_add_u64 v[18:19], v[18:19], 0, s[2:3]
	v_lshl_add_u64 v[20:21], v[20:21], 0, s[4:5]
	s_waitcnt vmcnt(4)
	v_pk_mul_f32 v[24:25], v[46:47], s[10:11] op_sel_hi:[1,0]
	s_nop 0
	v_fma_f32 v25, -v24, v24, v25
	v_max_f32_e32 v25, 0, v25
	v_add_f32_e32 v25, 0x3727c5ac, v25
	v_cmp_gt_f32_e32 vcc, s11, v25
	s_waitcnt vmcnt(3)
	v_lshlrev_b32_e32 v46, 16, v42
	v_lshlrev_b32_e32 v52, 16, v45
	v_lshlrev_b32_e32 v50, 16, v44
	v_and_b32_e32 v51, 0xffff0000, v44
	v_sub_f32_e32 v44, v46, v24
	v_sub_f32_e32 v46, v52, v24
	v_mul_f32_e32 v52, 0x4f800000, v25
	v_cndmask_b32_e32 v25, v25, v52, vcc
	v_sqrt_f32_e32 v52, v25
	v_and_b32_e32 v47, 0xffff0000, v42
	v_and_b32_e32 v53, 0xffff0000, v45
	v_sub_f32_e32 v45, v47, v24
	v_sub_f32_e32 v47, v53, v24
	v_add_u32_e32 v53, -1, v52
	v_add_u32_e32 v54, 1, v52
	v_fma_f32 v55, -v53, v52, v25
	v_fma_f32 v56, -v54, v52, v25
	v_cmp_ge_f32_e64 s[0:1], 0, v55
	v_lshlrev_b32_e32 v42, 16, v43
	v_and_b32_e32 v43, 0xffff0000, v43
	v_cndmask_b32_e64 v52, v52, v53, s[0:1]
	v_cmp_lt_f32_e64 s[0:1], 0, v56
	v_sub_f32_e32 v43, v43, v24
	v_sub_f32_e32 v42, v42, v24
	v_cndmask_b32_e64 v52, v52, v54, s[0:1]
	v_mul_f32_e32 v53, 0x37800000, v52
	v_cndmask_b32_e32 v52, v52, v53, vcc
	v_cmp_class_f32_e32 vcc, v25, v1
	v_sub_f32_e32 v51, v51, v24
	v_sub_f32_e32 v50, v50, v24
	v_cndmask_b32_e32 v25, v52, v25, vcc
	v_div_scale_f32 v52, s[0:1], v25, v25, 1.0
	v_rcp_f32_e32 v54, v52
	v_div_scale_f32 v53, vcc, 1.0, v25, 1.0
	v_fma_f32 v55, -v52, v54, 1.0
	v_fmac_f32_e32 v54, v55, v54
	v_mul_f32_e32 v55, v53, v54
	v_fma_f32 v56, -v52, v55, v53
	v_fmac_f32_e32 v55, v56, v54
	v_fma_f32 v52, -v52, v55, v53
	v_div_fmas_f32 v52, v52, v54, v55
	v_div_fixup_f32 v52, v52, v25, 1.0
	v_pk_mul_f32 v[44:45], v[52:53], v[44:45] op_sel_hi:[0,1]
	v_pk_mul_f32 v[42:43], v[52:53], v[42:43] op_sel_hi:[0,1]
	v_pk_mul_f32 v[50:51], v[52:53], v[50:51] op_sel_hi:[0,1]
	v_pk_mul_f32 v[46:47], v[52:53], v[46:47] op_sel_hi:[0,1]
	v_pk_fma_f32 v[32:33], v[70:71], v[42:43], v[78:79]
	v_pk_fma_f32 v[30:31], v[68:69], v[44:45], v[76:77]
	v_pk_fma_f32 v[28:29], v[66:67], v[46:47], v[74:75]
	v_pk_fma_f32 v[26:27], v[64:65], v[50:51], v[72:73]
	global_store_dwordx4 v[22:23], v[30:33], off offset:-4096
	global_store_dwordx4 v[22:23], v[26:29], off offset:-4080
	s_nop 0
	s_nop 0
	s_nop 0
	s_nop 0
	s_nop 0
	s_nop 0
	v_cmp_lt_i32_e32 vcc, s13, v0
	s_or_b64 s[8:9], vcc, s[8:9]
	s_waitcnt vmcnt(4)
	v_lshlrev_b32_e32 v25, 16, v128
	v_and_b32_e32 v46, 0xffff0000, v128
	v_lshlrev_b32_e32 v26, 16, v129
	v_and_b32_e32 v27, 0xffff0000, v129
	v_lshlrev_b32_e32 v50, 16, v130
	v_and_b32_e32 v51, 0xffff0000, v130
	v_lshlrev_b32_e32 v53, 16, v131
	v_and_b32_e32 v47, 0xffff0000, v131
	v_sub_f32_e32 v27, v27, v24
	v_sub_f32_e32 v26, v26, v24
	v_sub_f32_e32 v29, v46, v24
	v_sub_f32_e32 v28, v25, v24
	v_sub_f32_e32 v47, v47, v24
	v_sub_f32_e32 v46, v53, v24
	v_sub_f32_e32 v51, v51, v24
	v_sub_f32_e32 v50, v50, v24
	v_pk_mul_f32 v[54:55], v[52:53], v[28:29] op_sel_hi:[0,1]
	v_pk_mul_f32 v[26:27], v[52:53], v[26:27] op_sel_hi:[0,1]
	v_pk_mul_f32 v[50:51], v[52:53], v[50:51] op_sel_hi:[0,1]
	v_pk_mul_f32 v[46:47], v[52:53], v[46:47] op_sel_hi:[0,1]
	s_nop 0
	v_pk_fma_f32 v[28:29], v[86:87], v[26:27], v[82:83]
	v_pk_fma_f32 v[26:27], v[84:85], v[54:55], v[80:81]
	s_nop 0
	v_pk_fma_f32 v[32:33], v[90:91], v[46:47], v[94:95]
	v_pk_fma_f32 v[30:31], v[88:89], v[50:51], v[92:93]
	global_store_dwordx4 v[22:23], v[26:29], off offset:-2048
	global_store_dwordx4 v[22:23], v[30:33], off offset:-2032
	s_nop 0
	s_nop 0
	s_nop 0
	s_nop 0
	s_nop 0
	s_nop 0
	s_waitcnt vmcnt(5)
	v_lshlrev_b32_e32 v25, 16, v132
	v_and_b32_e32 v46, 0xffff0000, v132
	v_lshlrev_b32_e32 v26, 16, v133
	v_and_b32_e32 v27, 0xffff0000, v133
	v_lshlrev_b32_e32 v50, 16, v134
	v_and_b32_e32 v51, 0xffff0000, v134
	v_lshlrev_b32_e32 v53, 16, v135
	v_and_b32_e32 v47, 0xffff0000, v135
	v_sub_f32_e32 v27, v27, v24
	v_sub_f32_e32 v26, v26, v24
	v_sub_f32_e32 v29, v46, v24
	v_sub_f32_e32 v28, v25, v24
	v_sub_f32_e32 v47, v47, v24
	v_sub_f32_e32 v46, v53, v24
	v_sub_f32_e32 v51, v51, v24
	v_sub_f32_e32 v50, v50, v24
	v_pk_mul_f32 v[54:55], v[52:53], v[28:29] op_sel_hi:[0,1]
	v_pk_mul_f32 v[26:27], v[52:53], v[26:27] op_sel_hi:[0,1]
	v_pk_mul_f32 v[50:51], v[52:53], v[50:51] op_sel_hi:[0,1]
	v_pk_mul_f32 v[46:47], v[52:53], v[46:47] op_sel_hi:[0,1]
	s_nop 0
	v_pk_fma_f32 v[28:29], v[102:103], v[26:27], v[98:99]
	v_pk_fma_f32 v[26:27], v[100:101], v[54:55], v[96:97]
	s_nop 0
	v_pk_fma_f32 v[32:33], v[106:107], v[46:47], v[110:111]
	v_pk_fma_f32 v[30:31], v[104:105], v[50:51], v[108:109]
	global_store_dwordx4 v[22:23], v[26:29], off
	global_store_dwordx4 v[22:23], v[30:33], off offset:16
	s_nop 0
	s_nop 0
	s_nop 0
	s_nop 0
	s_nop 0
	s_nop 0
	s_waitcnt vmcnt(6)
	v_lshlrev_b32_e32 v25, 16, v136
	v_and_b32_e32 v46, 0xffff0000, v136
	v_lshlrev_b32_e32 v26, 16, v137
	v_and_b32_e32 v27, 0xffff0000, v137
	v_lshlrev_b32_e32 v48, 16, v138
	v_and_b32_e32 v49, 0xffff0000, v138
	v_lshlrev_b32_e32 v50, 16, v139
	v_and_b32_e32 v47, 0xffff0000, v139
	v_sub_f32_e32 v27, v27, v24
	v_sub_f32_e32 v26, v26, v24
	v_sub_f32_e32 v29, v46, v24
	v_sub_f32_e32 v28, v25, v24
	v_sub_f32_e32 v47, v47, v24
	v_sub_f32_e32 v46, v50, v24
	v_sub_f32_e32 v25, v49, v24
	v_sub_f32_e32 v24, v48, v24
	v_pk_mul_f32 v[28:29], v[52:53], v[28:29] op_sel_hi:[0,1]
	v_pk_mul_f32 v[26:27], v[52:53], v[26:27] op_sel_hi:[0,1]
	v_pk_mul_f32 v[48:49], v[52:53], v[24:25] op_sel_hi:[0,1]
	v_pk_mul_f32 v[46:47], v[52:53], v[46:47] op_sel_hi:[0,1]
	s_nop 0
	v_pk_fma_f32 v[26:27], v[118:119], v[26:27], v[114:115]
	v_pk_fma_f32 v[24:25], v[116:117], v[28:29], v[112:113]
	s_nop 0
	v_pk_fma_f32 v[30:31], v[122:123], v[46:47], v[126:127]
	v_pk_fma_f32 v[28:29], v[120:121], v[48:49], v[124:125]
	global_store_dwordx4 v[22:23], v[24:27], off offset:2048
	global_store_dwordx4 v[22:23], v[28:31], off offset:2064
	v_lshl_add_u64 v[22:23], v[22:23], 0, s[6:7]
	s_andn2_b64 exec, exec, s[8:9]
	s_cbranch_execnz .LBB0_1549
